# panel barrier: the L1 invalidate is issued right after the arrival (all other waves of the workgroup are parked at the closing barrier) so its latency overlaps the wait for the panel peers
# baseline (speedup 1.0000x reference)
; __device__ __forceinline__ unsigned xb_ld(unsigned* p)              { return __hip_atomic_load(p, __ATOMIC_RELAXED, __HIP_MEMORY_SCOPE_AGENT); }
; __device__ __forceinline__ unsigned xb_add(unsigned* p, unsigned v) { return __hip_atomic_fetch_add(p, v, __ATOMIC_RELAXED, __HIP_MEMORY_SCOPE_AGENT); }
; #define XB_SPIN(cond, bar) do { unsigned _sp = 0; while (cond) { __builtin_amdgcn_s_sleep(1); \
;     if ((++_sp & 255u) == 0u) { if (xb_ld(&(bar)[XB_TMO])) break; if (_sp > XB_SPIN_CAP) { atomicAdd(&(bar)[XB_TMO], 1u); break; } } } } while (0)
; __device__ __forceinline__ void xcd_barrier(const XcdBarrier& b) {
;     asm volatile("s_waitcnt vmcnt(0)" ::: "memory");
;     __syncthreads();
;     if (threadIdx.x == 0) {
;         unsigned* bar = b.bar;
;         __builtin_amdgcn_s_waitcnt(0);
;         unsigned nloc = b.st[0], nx = b.st[1];
;         if (nloc == 0u) { xcd_barrier_complete(bar, b.x, nloc, nx); b.st[0] = nloc; b.st[1] = nx; }
;         const unsigned old = xb_add(&bar[XB_XSUB(b.x)], 1u);
;         const unsigned gen = old / nloc;
;         if (old + 1u == (gen + 1u) * nloc) {
;             __builtin_amdgcn_fence(__ATOMIC_RELEASE, "agent");
;             asm volatile("s_waitcnt vmcnt(0)" ::: "memory");
;             const unsigned og = xb_add(&bar[XB_TOP], 1u);
;             const unsigned tg = og / nx;
;             if (og + 1u == (tg + 1u) * nx) xb_add(&bar[XB_TOPGEN], 1u);
;             else XB_SPIN(xb_ld(&bar[XB_TOPGEN]) == tg, bar);
;             __builtin_amdgcn_fence(__ATOMIC_ACQUIRE, "agent");
;             xb_add(&bar[XB_XGEN(b.x)], 1u);
;             asm volatile("s_waitcnt vmcnt(0)" ::: "memory");
;         } else {
;             XB_SPIN(xb_ld(&bar[XB_XGEN(b.x)]) == gen, bar);
;             __builtin_amdgcn_fence(__ATOMIC_ACQUIRE, "agent");
;             asm volatile("s_waitcnt vmcnt(0)" ::: "memory");
;         }
;     }
;     __syncthreads();
; }
; __global__ void __launch_bounds__(512, 2) fwd_kernel(Args A_unused) {
;     ...
;         if (ph + 1 < ph_hi) {
;             if (ph_lo < 0) grid.sync();
;             xcd_barrier(xbar);
;         }
.LBB0_893:
	v_mov_b32_e32 v1, 0x20018
	ds_read_b32 v1, v1
	v_readlane_b32 s10, v238, 0
	v_readlane_b32 s13, v237, 62
	s_waitcnt vmcnt(0) lgkmcnt(0)
	s_nop 0
	v_readfirstlane_b32 s11, v1
	s_nop 3
	s_mul_i32 s11, s11, 0xcf9c
	s_bitcmp1_b32 s11, s10
	s_cbranch_scc0 .Lmy_global_bar
	s_lshl_b32 s12, 2, s10
	s_add_i32 s12, s12, -1
	s_and_b32 s12, s12, 0xcf9c
	s_bcnt1_i32_b32 s12, s12
	s_lshl_b32 s12, s12, 2
	s_and_b32 s6, s13, 7
	s_lshl_b32 s6, s6, 3
	s_bfe_u32 s7, s13, 0x30003
	s_add_i32 s13, s6, s7
	s_mul_i32 s6, s13, 10
	s_mul_i32 s6, s6, 0x1746
	s_lshr_b32 s6, s6, 16
	s_add_i32 s7, s6, 1
	s_min_u32 s7, s7, s13
	s_cmp_eq_u32 s10, 4
	s_cselect_b32 s11, 1, 0
	s_cmp_eq_u32 s10, 11
	s_cselect_b32 s11, 1, s11
	s_cmp_eq_u32 s11, 1
	s_cselect_b32 s6, s6, s13
	s_cselect_b32 s7, s7, s13
	s_lshl_b32 s13, s13, 6
	s_lshl_b32 s6, s6, 6
	s_lshl_b32 s7, s7, 6
	s_addk_i32 s13, 0x1000
	s_addk_i32 s6, 0x1000
	s_addk_i32 s7, 0x1000
	v_mov_b32_e32 v1, s13
	v_mov_b32_e32 v2, s6
	v_mov_b32_e32 v3, s7
	v_readlane_b32 s6, v238, 30
	v_readlane_b32 s7, v238, 31
	v_mov_b32_e32 v8, 1
	s_mov_b32 s13, 0
	s_sub_u32 s6, s6, 0x4200
	s_subb_u32 s7, s7, 0
	s_cmp_eq_u32 s10, 9
	s_cselect_b32 s11, 0x80, 0
	v_mov_b32_e32 v9, 0x4020
	s_nop 4
	global_atomic_add v1, v8, s[6:7]
	buffer_inv sc1
.Lmy_panel_spin:
	global_load_dword v4, v1, s[6:7] sc1
	global_load_dword v5, v2, s[6:7] sc1
	global_load_dword v6, v3, s[6:7] sc1
	global_load_dword v7, v9, s[6:7] sc1
	s_add_i32 s13, s13, 1
	s_waitcnt vmcnt(0)
	v_min3_u32 v4, v4, v5, v6
	v_cmp_le_u32_e64 s[14:15], s12, v4
	v_cmp_le_u32_e64 s[16:17], s11, v7
	s_nop 1
	s_and_b64 vcc, s[14:15], s[16:17]
	s_cbranch_vccnz .Lmy_panel_done
	s_cmp_lt_u32 s13, 0x200000
	s_cbranch_scc0 .Lmy_panel_done
	s_sleep 1
	s_branch .Lmy_panel_spin
.Lmy_panel_done:
	s_branch .Lmy_to_lbb8
.Lmy_global_bar:
	v_readlane_b32 s6, v237, 54
	s_waitcnt vmcnt(0) expcnt(0) lgkmcnt(0)
	s_nop 0
	v_mov_b32_e32 v1, s6
	ds_read_b32 v3, v1
	v_readlane_b32 s6, v237, 55
	s_waitcnt lgkmcnt(0)
	v_cmp_ne_u32_e32 vcc, 0, v3
	v_mov_b32_e32 v1, s6
	ds_read_b32 v2, v1
	s_cbranch_vccnz .LBB0_908
	s_mov_b32 s12, 1
	s_branch .LBB0_896
